# output epilogue fused into the V sweep: each token is finished right after its last run (x1 row prefetched when the run starts, gate row and final_g from an LDS copy), so the final stores spread over
# baseline (speedup 1.0000x reference)
; #define IT_ADVANCE() do { it_j += 4; while (it_j >= it_end) { if (it_done) break; ++it_tk; if (it_tk == 4) { it_tk = 0; ++it_p; if (it_p == 16) { it_done = true; it_p = 15; it_j = 0; it_end = 1; break; } } \
;             it_j = __builtin_amdgcn_readfirstlane(OFFS[(tb + it_tk) * 17 + it_p]); it_end = __builtin_amdgcn_readfirstlane(OFFS[(tb + it_tk) * 17 + it_p + 1]); } } while (0)
; __device__ __forceinline__ void peer_tile(const Args& A, LAS unsigned char* lds, int tile) {
;     ...
;             for (int q = 0; q < 8; ++q) oacc[tk][q] = (f32x2){0.f, 0.f}; }
;         int it_p = 0, it_tk = -1, it_j = 0, it_end = 0; bool it_done = false;
;     ...
;         u32x4 uA[4], vA[4], uB[4], vB[4]; float cgA = 0.f, suA = 0.f, svA = 0.f, cgB = 0.f, suB = 0.f, svB = 0.f;
; #pragma unroll
;         for (int k = 0; k < 4; ++k) { uA[k] = (u32x4){0u, 0u, 0u, 0u}; vA[k] = uA[k]; uB[k] = uA[k]; vB[k] = uA[k]; }
;         IT_ADVANCE();
;         LOAD_SET(uA, vA, cgA, suA, svA);
;     ...
;             const float* g2 = MOD + b * 6144 + 5120 + 16 * lane;
;             f32x4 xv[4]; float ss = 0.f;
; #pragma unroll
;             for (int j = 0; j < 4; ++j) { const f32x4 x1 = *(const f32x4*)(orow + 4 * j), gg = *(const f32x4*)(g2 + 4 * j);
;                 const f32x4 pe = (f32x4){oacc[tk][2 * j][0], oacc[tk][2 * j][1], oacc[tk][2 * j + 1][0], oacc[tk][2 * j + 1][1]};
;                 xv[j] = x1 + gg * pe; ss += (xv[j][0] * xv[j][0] + xv[j][1] * xv[j][1]) + (xv[j][2] * xv[j][2] + xv[j][3] * xv[j][3]); }
;             const float rstd = rsqrtf(wave_sum(ss) * (1.f / 1024.f) + 1e-6f);
; #pragma unroll
;             for (int j = 0; j < 4; ++j) { const f32x4 fg = *(const f32x4*)(A.final_g + 16 * lane + 4 * j); *(f32x4*)(orow + 4 * j) = xv[j] * rstd * fg; }
.LU_done:
	s_waitcnt vmcnt(0) lgkmcnt(0)
	v_mov_b64_e32 v[0:1], 0
	v_mov_b64_e32 v[2:3], 0
	v_mov_b64_e32 v[4:5], 0
	v_mov_b64_e32 v[6:7], 0
	v_mov_b64_e32 v[8:9], 0
	v_mov_b64_e32 v[10:11], 0
	v_mov_b64_e32 v[12:13], 0
	v_mov_b64_e32 v[14:15], 0
	v_mov_b64_e32 v[16:17], 0
	v_mov_b64_e32 v[18:19], 0
	v_mov_b64_e32 v[20:21], 0
	v_mov_b64_e32 v[22:23], 0
	v_mov_b64_e32 v[24:25], 0
	v_mov_b64_e32 v[26:27], 0
	v_mov_b64_e32 v[28:29], 0
	v_mov_b64_e32 v[30:31], 0
	v_mov_b64_e32 v[32:33], 0
	v_mov_b64_e32 v[34:35], 0
	v_mov_b64_e32 v[36:37], 0
	v_mov_b64_e32 v[38:39], 0
	v_mov_b64_e32 v[40:41], 0
	v_mov_b64_e32 v[42:43], 0
	v_mov_b64_e32 v[44:45], 0
	v_mov_b64_e32 v[46:47], 0
	v_mov_b64_e32 v[48:49], 0
	v_mov_b64_e32 v[50:51], 0
	v_mov_b64_e32 v[52:53], 0
	v_mov_b64_e32 v[54:55], 0
	v_mov_b64_e32 v[56:57], 0
	v_mov_b64_e32 v[58:59], 0
	v_mov_b64_e32 v[60:61], 0
	v_mov_b64_e32 v[62:63], 0
	v_mov_b64_e32 v[64:65], 0
	v_mov_b64_e32 v[66:67], 0
	v_mov_b64_e32 v[68:69], 0
	v_mov_b64_e32 v[70:71], 0
	v_mov_b64_e32 v[72:73], 0
	v_mov_b64_e32 v[74:75], 0
	v_mov_b64_e32 v[76:77], 0
	v_mov_b64_e32 v[78:79], 0
	v_mov_b64_e32 v[80:81], 0
	v_mov_b64_e32 v[82:83], 0
	v_mov_b64_e32 v[84:85], 0
	v_mov_b64_e32 v[86:87], 0
	v_mov_b64_e32 v[88:89], 0
	v_mov_b64_e32 v[90:91], 0
	v_mov_b64_e32 v[92:93], 0
	v_mov_b64_e32 v[94:95], 0
	v_mov_b64_e32 v[96:97], 0
	v_mov_b64_e32 v[98:99], 0
	v_mov_b64_e32 v[100:101], 0
	v_mov_b64_e32 v[102:103], 0
	v_mov_b64_e32 v[104:105], 0
	v_mov_b64_e32 v[106:107], 0
	v_mov_b64_e32 v[108:109], 0
	v_mov_b64_e32 v[110:111], 0
	v_mov_b64_e32 v[112:113], 0
	v_mov_b64_e32 v[114:115], 0
	v_mov_b64_e32 v[116:117], 0
	v_mov_b64_e32 v[118:119], 0
	v_mov_b64_e32 v[120:121], 0
	v_mov_b64_e32 v[122:123], 0
	v_mov_b64_e32 v[124:125], 0
	v_mov_b64_e32 v[126:127], 0
	s_add_i32 s20, s91, 3
	s_and_b32 s20, s20, -4
	s_waitcnt vmcnt(0) lgkmcnt(0)
	global_load_dwordx4 v[128:131], v246, s[82:83]
	global_load_dwordx4 v[132:135], v246, s[82:83] offset:16
	global_load_dwordx4 v[136:139], v246, s[82:83] offset:32
	global_load_dwordx4 v[140:143], v246, s[82:83] offset:48
	global_load_dwordx4 v[144:147], v246, s[46:47]
	global_load_dwordx4 v[148:151], v246, s[46:47] offset:16
	global_load_dwordx4 v[152:155], v246, s[46:47] offset:32
	global_load_dwordx4 v[156:159], v246, s[46:47] offset:48
	s_lshl_b32 s0, s76, 10
	s_add_i32 s0, s0, 0x11000
	v_add_u32_e32 v211, s0, v240
	s_waitcnt vmcnt(0)
	ds_write_b128 v211, v[128:131] offset:0
	ds_write_b128 v211, v[132:135] offset:1024
	ds_write_b128 v211, v[136:139] offset:2048
	ds_write_b128 v211, v[140:143] offset:3072
	ds_write_b128 v211, v[144:147] offset:4096
	ds_write_b128 v211, v[148:151] offset:5120
	ds_write_b128 v211, v[152:155] offset:6144
	ds_write_b128 v211, v[156:159] offset:7168
	s_mov_b32 s88, 0
	v_mov_b32_e32 v213, s22
	v_mov_b32_e32 v233, v240
	v_mov_b32_e32 v235, v240
	v_mov_b32_e32 v237, v240
	v_mov_b32_e32 v239, v240
	ds_read_b32 v232, v213 offset:0
	ds_read_b32 v234, v213 offset:4
	ds_read_b32 v236, v213 offset:8
	ds_read_b32 v238, v213 offset:12
	s_waitcnt lgkmcnt(0)
	buffer_load_dwordx4 v[128:131], v[232:233], s[60:63], 0 idxen offen
	buffer_load_dwordx4 v[132:135], v[234:235], s[60:63], 0 idxen offen
	buffer_load_dwordx4 v[136:139], v[236:237], s[60:63], 0 idxen offen
	buffer_load_dwordx4 v[140:143], v[238:239], s[60:63], 0 idxen offen
	ds_read_b32 v232, v213 offset:16
	ds_read_b32 v234, v213 offset:20
	ds_read_b32 v236, v213 offset:24
	ds_read_b32 v238, v213 offset:28
	s_waitcnt lgkmcnt(0)
	buffer_load_dwordx4 v[144:147], v[232:233], s[60:63], 0 idxen offen
	buffer_load_dwordx4 v[148:151], v[234:235], s[60:63], 0 idxen offen
	buffer_load_dwordx4 v[152:155], v[236:237], s[60:63], 0 idxen offen
	buffer_load_dwordx4 v[156:159], v[238:239], s[60:63], 0 idxen offen
	ds_read_b32 v232, v213 offset:32
	ds_read_b32 v234, v213 offset:36
	ds_read_b32 v236, v213 offset:40
	ds_read_b32 v238, v213 offset:44
	s_waitcnt lgkmcnt(0)
	buffer_load_dwordx4 v[160:163], v[232:233], s[60:63], 0 idxen offen
	buffer_load_dwordx4 v[164:167], v[234:235], s[60:63], 0 idxen offen
	buffer_load_dwordx4 v[168:171], v[236:237], s[60:63], 0 idxen offen
	buffer_load_dwordx4 v[172:175], v[238:239], s[60:63], 0 idxen offen
	ds_read_b128 v[248:251], v213 offset:4992
	ds_read_b32 v232, v213 offset:48
	ds_read_b32 v234, v213 offset:52
	ds_read_b32 v236, v213 offset:56
	ds_read_b32 v238, v213 offset:60
	s_mov_b32 s21, 0
	s_mov_b32 s89, -1
	s_mov_b32 s86, 0
	s_branch .LV_sw0

; __device__ __forceinline__ void peer_tile(const Args& A, LAS unsigned char* lds, int tile) {
;     ...
;         for (int p = 0; p < 16; ++p) {
; #pragma unroll
;             for (int tk = 0; tk < 4; ++tk) {
;                 const int tl = tb + tk;
;                 const int beg = __builtin_amdgcn_readfirstlane(OFFS[tl * 17 + p]), end = __builtin_amdgcn_readfirstlane(OFFS[tl * 17 + p + 1]);
;     ...
;         for (int tk = 0; tk < 4; ++tk) {
;             const size_t m = (size_t)tile * 64 + tb + tk; const int b = (int)(m >> 11);
.LV_sw0:
	s_sub_i32 s0, s89, 56
	s_cmp_lt_u32 s0, 8
	s_cbranch_scc0 .LV_sw0_c
	s_mov_b32 s87, 0
	s_mov_b32 s23, s0
	s_cmp_ge_u32 s23, 4
	s_cbranch_scc1 .LV_sw0_e_h
	s_cmp_ge_u32 s23, 2
	s_cbranch_scc1 .LV_sw0_e_23
	s_cmp_eq_u32 s23, 0
	s_cbranch_scc1 .LV_epi_t0
	s_branch .LV_epi_t1

; __device__ __forceinline__ void peer_tile(const Args& A, LAS unsigned char* lds, int tile) {
;     ...
;         for (int p = 0; p < 16; ++p) {
; #pragma unroll
;             for (int tk = 0; tk < 4; ++tk) {
;                 const int tl = tb + tk;
;                 const int beg = __builtin_amdgcn_readfirstlane(OFFS[tl * 17 + p]), end = __builtin_amdgcn_readfirstlane(OFFS[tl * 17 + p + 1]);
;     ...
;             const size_t m = (size_t)tile * 64 + tb + tk; const int b = (int)(m >> 11);
;             float* orow = A.out + m * 1024 + 16 * lane;
;             const float* g2 = MOD + b * 6144 + 5120 + 16 * lane;
;             f32x4 xv[4]; float ss = 0.f;
; #pragma unroll
;             for (int j = 0; j < 4; ++j) { const f32x4 x1 = *(const f32x4*)(orow + 4 * j), gg = *(const f32x4*)(g2 + 4 * j);
.LV_sw0_c:
	s_add_i32 s89, s89, 1
	s_cmp_ge_u32 s89, 64
	s_cbranch_scc1 .LV_sw0_end
	s_and_b32 s0, s89, 7
	s_lshr_b32 s1, s89, 3
	s_lshl_b32 s0, s0, 3
	s_or_b32 s0, s0, s1
	s_nop 0
	v_readlane_b32 s90, v212, s0
	s_sub_i32 s0, s89, 56
	s_cmp_lt_u32 s0, 8
	s_cbranch_scc0 .LV_sw0_nx
	s_add_i32 s0, s0, s77
	s_lshl_b32 s0, s0, 12
	s_add_u32 s24, s48, s0
	s_addc_u32 s25, s49, 0
	global_load_dwordx4 v[192:195], v246, s[24:25]
	global_load_dwordx4 v[196:199], v246, s[24:25] offset:16
	global_load_dwordx4 v[200:203], v246, s[24:25] offset:32
	global_load_dwordx4 v[204:207], v246, s[24:25] offset:48
	s_mov_b32 s88, s90
.LV_sw0_nx:
	s_and_b32 s23, s89, 7
	s_cmp_eq_u32 s90, 0
	s_cbranch_scc1 .LV_sw0
	s_cmp_ge_u32 s23, 4
	s_cbranch_scc1 .LV_sw0_h
	s_cmp_ge_u32 s23, 2
	s_cbranch_scc1 .LV_sw0_23
	s_cmp_eq_u32 s23, 0
	s_cbranch_scc1 .LV_t0_s0
	s_branch .LV_t1_s0

; __device__ __forceinline__ void peer_tile(const Args& A, LAS unsigned char* lds, int tile) {
;     ...
;         for (int p = 0; p < 16; ++p) {
; #pragma unroll
;             for (int tk = 0; tk < 4; ++tk) {
;                 const int tl = tb + tk;
;                 const int beg = __builtin_amdgcn_readfirstlane(OFFS[tl * 17 + p]), end = __builtin_amdgcn_readfirstlane(OFFS[tl * 17 + p + 1]);
;     ...
;         for (int tk = 0; tk < 4; ++tk) {
;             const size_t m = (size_t)tile * 64 + tb + tk; const int b = (int)(m >> 11);
.LV_sw1:
	s_sub_i32 s0, s89, 56
	s_cmp_lt_u32 s0, 8
	s_cbranch_scc0 .LV_sw1_c
	s_mov_b32 s87, 1
	s_mov_b32 s23, s0
	s_cmp_ge_u32 s23, 4
	s_cbranch_scc1 .LV_sw1_e_h
	s_cmp_ge_u32 s23, 2
	s_cbranch_scc1 .LV_sw1_e_23
	s_cmp_eq_u32 s23, 0
	s_cbranch_scc1 .LV_epi_t0
	s_branch .LV_epi_t1

; __device__ __forceinline__ void peer_tile(const Args& A, LAS unsigned char* lds, int tile) {
;     ...
;         for (int p = 0; p < 16; ++p) {
; #pragma unroll
;             for (int tk = 0; tk < 4; ++tk) {
;                 const int tl = tb + tk;
;                 const int beg = __builtin_amdgcn_readfirstlane(OFFS[tl * 17 + p]), end = __builtin_amdgcn_readfirstlane(OFFS[tl * 17 + p + 1]);
;     ...
;         for (int tk = 0; tk < 4; ++tk) {
;             const size_t m = (size_t)tile * 64 + tb + tk; const int b = (int)(m >> 11);
.LV_sw2:
	s_sub_i32 s0, s89, 56
	s_cmp_lt_u32 s0, 8
	s_cbranch_scc0 .LV_sw2_c
	s_mov_b32 s87, 2
	s_mov_b32 s23, s0
	s_cmp_ge_u32 s23, 4
	s_cbranch_scc1 .LV_sw2_e_h
	s_cmp_ge_u32 s23, 2
	s_cbranch_scc1 .LV_sw2_e_23
	s_cmp_eq_u32 s23, 0
	s_cbranch_scc1 .LV_epi_t0
	s_branch .LV_epi_t1

; __device__ __forceinline__ void peer_tile(const Args& A, LAS unsigned char* lds, int tile) {
;     ...
;         for (int p = 0; p < 16; ++p) {
; #pragma unroll
;             for (int tk = 0; tk < 4; ++tk) {
;                 const int tl = tb + tk;
;                 const int beg = __builtin_amdgcn_readfirstlane(OFFS[tl * 17 + p]), end = __builtin_amdgcn_readfirstlane(OFFS[tl * 17 + p + 1]);
;     ...
;         for (int tk = 0; tk < 4; ++tk) {
;             const size_t m = (size_t)tile * 64 + tb + tk; const int b = (int)(m >> 11);
.LV_sw3:
	s_sub_i32 s0, s89, 56
	s_cmp_lt_u32 s0, 8
	s_cbranch_scc0 .LV_sw3_c
	s_mov_b32 s87, 3
	s_mov_b32 s23, s0
	s_cmp_ge_u32 s23, 4
	s_cbranch_scc1 .LV_sw3_e_h
	s_cmp_ge_u32 s23, 2
	s_cbranch_scc1 .LV_sw3_e_23
	s_cmp_eq_u32 s23, 0
	s_cbranch_scc1 .LV_epi_t0
	s_branch .LV_epi_t1

; __device__ __forceinline__ void peer_tile(const Args& A, LAS unsigned char* lds, int tile) {
;     ...
;         for (int tk = 0; tk < 4; ++tk) {
;             const size_t m = (size_t)tile * 64 + tb + tk; const int b = (int)(m >> 11);
;             float* orow = A.out + m * 1024 + 16 * lane;
;             const float* g2 = MOD + b * 6144 + 5120 + 16 * lane;
;             f32x4 xv[4]; float ss = 0.f;
; #pragma unroll
;             for (int j = 0; j < 4; ++j) { const f32x4 x1 = *(const f32x4*)(orow + 4 * j), gg = *(const f32x4*)(g2 + 4 * j);
;                 const f32x4 pe = (f32x4){oacc[tk][2 * j][0], oacc[tk][2 * j][1], oacc[tk][2 * j + 1][0], oacc[tk][2 * j + 1][1]};
;                 xv[j] = x1 + gg * pe; ss += (xv[j][0] * xv[j][0] + xv[j][1] * xv[j][1]) + (xv[j][2] * xv[j][2] + xv[j][3] * xv[j][3]); }
;             const float rstd = rsqrtf(wave_sum(ss) * (1.f / 1024.f) + 1e-6f);
; #pragma unroll
;             for (int j = 0; j < 4; ++j) { const f32x4 fg = *(const f32x4*)(A.final_g + 16 * lane + 4 * j); *(f32x4*)(orow + 4 * j) = xv[j] * rstd * fg; }
.LV_epi_t0:
	s_cmp_ge_u32 s88, 3
	s_cbranch_scc1 .LV_epi_t0_w12
	s_cmp_eq_u32 s88, 2
	s_cbranch_scc1 .LV_epi_t0_w8
	s_cmp_eq_u32 s88, 1
	s_cbranch_scc1 .LV_epi_t0_w4
	s_waitcnt vmcnt(0)
	s_branch .LV_epi_t0_go
.LV_epi_t0_w4:
	s_waitcnt vmcnt(4)
	s_branch .LV_epi_t0_go
.LV_epi_t0_w8:
	s_waitcnt vmcnt(8)
	s_branch .LV_epi_t0_go
.LV_epi_t0_w12:
	s_waitcnt vmcnt(12)
.LV_epi_t0_go:
	ds_read_b128 v[216:219], v211 offset:0
	ds_read_b128 v[220:223], v211 offset:1024
	ds_read_b128 v[224:227], v211 offset:2048
	ds_read_b128 v[228:231], v211 offset:3072
	s_waitcnt lgkmcnt(0)
	v_pk_fma_f32 v[0:1], v[0:1], v[216:217], v[192:193]
	v_pk_fma_f32 v[2:3], v[2:3], v[218:219], v[194:195]
	v_pk_fma_f32 v[4:5], v[4:5], v[220:221], v[196:197]
	v_pk_fma_f32 v[6:7], v[6:7], v[222:223], v[198:199]
	v_pk_fma_f32 v[8:9], v[8:9], v[224:225], v[200:201]
	v_pk_fma_f32 v[10:11], v[10:11], v[226:227], v[202:203]
	v_pk_fma_f32 v[12:13], v[12:13], v[228:229], v[204:205]
	v_pk_fma_f32 v[14:15], v[14:15], v[230:231], v[206:207]
	ds_read_b128 v[216:219], v211 offset:4096
	ds_read_b128 v[220:223], v211 offset:5120
	ds_read_b128 v[224:227], v211 offset:6144
	ds_read_b128 v[228:231], v211 offset:7168
	v_pk_mul_f32 v[208:209], v[0:1], v[0:1]
	v_pk_fma_f32 v[208:209], v[2:3], v[2:3], v[208:209]
	v_pk_fma_f32 v[208:209], v[4:5], v[4:5], v[208:209]
	v_pk_fma_f32 v[208:209], v[6:7], v[6:7], v[208:209]
	v_pk_fma_f32 v[208:209], v[8:9], v[8:9], v[208:209]
	v_pk_fma_f32 v[208:209], v[10:11], v[10:11], v[208:209]
	v_pk_fma_f32 v[208:209], v[12:13], v[12:13], v[208:209]
	v_pk_fma_f32 v[208:209], v[14:15], v[14:15], v[208:209]
	v_add_f32_e32 v208, v208, v209
	v_mov_b32_e32 v210, v208
	s_nop 1
	v_permlane32_swap_b32_e32 v208, v210
	v_add_f32_e32 v208, v208, v210
	v_mov_b32_e32 v210, v208
	s_nop 1
	v_permlane16_swap_b32_e32 v208, v210
	v_add_f32_e32 v208, v208, v210
	s_nop 1
	v_add_f32_dpp v208, v208, v208 quad_perm:[1,0,3,2] row_mask:0xf bank_mask:0xf bound_ctrl:1
	s_nop 1
	v_add_f32_dpp v208, v208, v208 quad_perm:[2,3,0,1] row_mask:0xf bank_mask:0xf bound_ctrl:1
	s_nop 1
	v_add_f32_dpp v208, v208, v208 row_half_mirror row_mask:0xf bank_mask:0xf bound_ctrl:1
	s_nop 1
	v_add_f32_dpp v208, v208, v208 row_mirror row_mask:0xf bank_mask:0xf bound_ctrl:1
	v_fmamk_f32 v208, v208, 0x3a800000, v243
	v_rsq_f32_e32 v208, v208
	s_waitcnt lgkmcnt(0)
	v_pk_mul_f32 v[192:193], v[0:1], v[208:209] op_sel_hi:[1,0]
	v_pk_mul_f32 v[194:195], v[2:3], v[208:209] op_sel_hi:[1,0]
	v_pk_mul_f32 v[196:197], v[4:5], v[208:209] op_sel_hi:[1,0]
	v_pk_mul_f32 v[198:199], v[6:7], v[208:209] op_sel_hi:[1,0]
	v_pk_mul_f32 v[200:201], v[8:9], v[208:209] op_sel_hi:[1,0]
	v_pk_mul_f32 v[202:203], v[10:11], v[208:209] op_sel_hi:[1,0]
	v_pk_mul_f32 v[204:205], v[12:13], v[208:209] op_sel_hi:[1,0]
	v_pk_mul_f32 v[206:207], v[14:15], v[208:209] op_sel_hi:[1,0]
	v_pk_mul_f32 v[192:193], v[216:217], v[192:193]
	v_pk_mul_f32 v[194:195], v[218:219], v[194:195]
	v_pk_mul_f32 v[196:197], v[220:221], v[196:197]
	v_pk_mul_f32 v[198:199], v[222:223], v[198:199]
	v_pk_mul_f32 v[200:201], v[224:225], v[200:201]
	v_pk_mul_f32 v[202:203], v[226:227], v[202:203]
	v_pk_mul_f32 v[204:205], v[228:229], v[204:205]
	v_pk_mul_f32 v[206:207], v[230:231], v[206:207]
	global_store_dwordx4 v246, v[192:195], s[24:25]
	global_store_dwordx4 v246, v[196:199], s[24:25] offset:16
	global_store_dwordx4 v246, v[200:203], s[24:25] offset:32
	global_store_dwordx4 v246, v[204:207], s[24:25] offset:48
	s_nop 1
	s_cmp_eq_u32 s87, 0
	s_cbranch_scc1 .LV_sw0_c
	s_cmp_eq_u32 s87, 1
	s_cbranch_scc1 .LV_sw1_c
	s_cmp_eq_u32 s87, 2
	s_cbranch_scc1 .LV_sw2_c
	s_branch .LV_sw3_c

; __device__ __forceinline__ void peer_tile(const Args& A, LAS unsigned char* lds, int tile) {
;     ...
;         for (int tk = 0; tk < 4; ++tk) {
;             const size_t m = (size_t)tile * 64 + tb + tk; const int b = (int)(m >> 11);
;             float* orow = A.out + m * 1024 + 16 * lane;
;             const float* g2 = MOD + b * 6144 + 5120 + 16 * lane;
;             f32x4 xv[4]; float ss = 0.f;
; #pragma unroll
;             for (int j = 0; j < 4; ++j) { const f32x4 x1 = *(const f32x4*)(orow + 4 * j), gg = *(const f32x4*)(g2 + 4 * j);
;                 const f32x4 pe = (f32x4){oacc[tk][2 * j][0], oacc[tk][2 * j][1], oacc[tk][2 * j + 1][0], oacc[tk][2 * j + 1][1]};
;                 xv[j] = x1 + gg * pe; ss += (xv[j][0] * xv[j][0] + xv[j][1] * xv[j][1]) + (xv[j][2] * xv[j][2] + xv[j][3] * xv[j][3]); }
;             const float rstd = rsqrtf(wave_sum(ss) * (1.f / 1024.f) + 1e-6f);
; #pragma unroll
;             for (int j = 0; j < 4; ++j) { const f32x4 fg = *(const f32x4*)(A.final_g + 16 * lane + 4 * j); *(f32x4*)(orow + 4 * j) = xv[j] * rstd * fg; }
.LV_epi_t1_go:
	ds_read_b128 v[216:219], v211 offset:0
	ds_read_b128 v[220:223], v211 offset:1024
	ds_read_b128 v[224:227], v211 offset:2048
	ds_read_b128 v[228:231], v211 offset:3072
	s_waitcnt lgkmcnt(0)
	v_pk_fma_f32 v[16:17], v[16:17], v[216:217], v[192:193]
	v_pk_fma_f32 v[18:19], v[18:19], v[218:219], v[194:195]
	v_pk_fma_f32 v[20:21], v[20:21], v[220:221], v[196:197]
	v_pk_fma_f32 v[22:23], v[22:23], v[222:223], v[198:199]
	v_pk_fma_f32 v[24:25], v[24:25], v[224:225], v[200:201]
	v_pk_fma_f32 v[26:27], v[26:27], v[226:227], v[202:203]
	v_pk_fma_f32 v[28:29], v[28:29], v[228:229], v[204:205]
	v_pk_fma_f32 v[30:31], v[30:31], v[230:231], v[206:207]
	ds_read_b128 v[216:219], v211 offset:4096
	ds_read_b128 v[220:223], v211 offset:5120
	ds_read_b128 v[224:227], v211 offset:6144
	ds_read_b128 v[228:231], v211 offset:7168
	v_pk_mul_f32 v[208:209], v[16:17], v[16:17]
	v_pk_fma_f32 v[208:209], v[18:19], v[18:19], v[208:209]
	v_pk_fma_f32 v[208:209], v[20:21], v[20:21], v[208:209]
	v_pk_fma_f32 v[208:209], v[22:23], v[22:23], v[208:209]
	v_pk_fma_f32 v[208:209], v[24:25], v[24:25], v[208:209]
	v_pk_fma_f32 v[208:209], v[26:27], v[26:27], v[208:209]
	v_pk_fma_f32 v[208:209], v[28:29], v[28:29], v[208:209]
	v_pk_fma_f32 v[208:209], v[30:31], v[30:31], v[208:209]
	v_add_f32_e32 v208, v208, v209
	v_mov_b32_e32 v210, v208
	s_nop 1
	v_permlane32_swap_b32_e32 v208, v210
	v_add_f32_e32 v208, v208, v210
	v_mov_b32_e32 v210, v208
	s_nop 1
	v_permlane16_swap_b32_e32 v208, v210
	v_add_f32_e32 v208, v208, v210
	s_nop 1
	v_add_f32_dpp v208, v208, v208 quad_perm:[1,0,3,2] row_mask:0xf bank_mask:0xf bound_ctrl:1
	s_nop 1
	v_add_f32_dpp v208, v208, v208 quad_perm:[2,3,0,1] row_mask:0xf bank_mask:0xf bound_ctrl:1
	s_nop 1
	v_add_f32_dpp v208, v208, v208 row_half_mirror row_mask:0xf bank_mask:0xf bound_ctrl:1
	s_nop 1
	v_add_f32_dpp v208, v208, v208 row_mirror row_mask:0xf bank_mask:0xf bound_ctrl:1
	v_fmamk_f32 v208, v208, 0x3a800000, v243
	v_rsq_f32_e32 v208, v208
	s_waitcnt lgkmcnt(0)
	v_pk_mul_f32 v[192:193], v[16:17], v[208:209] op_sel_hi:[1,0]
	v_pk_mul_f32 v[194:195], v[18:19], v[208:209] op_sel_hi:[1,0]
	v_pk_mul_f32 v[196:197], v[20:21], v[208:209] op_sel_hi:[1,0]
	v_pk_mul_f32 v[198:199], v[22:23], v[208:209] op_sel_hi:[1,0]
	v_pk_mul_f32 v[200:201], v[24:25], v[208:209] op_sel_hi:[1,0]
	v_pk_mul_f32 v[202:203], v[26:27], v[208:209] op_sel_hi:[1,0]
	v_pk_mul_f32 v[204:205], v[28:29], v[208:209] op_sel_hi:[1,0]
	v_pk_mul_f32 v[206:207], v[30:31], v[208:209] op_sel_hi:[1,0]
	v_pk_mul_f32 v[192:193], v[216:217], v[192:193]
	v_pk_mul_f32 v[194:195], v[218:219], v[194:195]
	v_pk_mul_f32 v[196:197], v[220:221], v[196:197]
	v_pk_mul_f32 v[198:199], v[222:223], v[198:199]
	v_pk_mul_f32 v[200:201], v[224:225], v[200:201]
	v_pk_mul_f32 v[202:203], v[226:227], v[202:203]
	v_pk_mul_f32 v[204:205], v[228:229], v[204:205]
	v_pk_mul_f32 v[206:207], v[230:231], v[206:207]
	global_store_dwordx4 v246, v[192:195], s[24:25]
	global_store_dwordx4 v246, v[196:199], s[24:25] offset:16
	global_store_dwordx4 v246, v[200:203], s[24:25] offset:32
	global_store_dwordx4 v246, v[204:207], s[24:25] offset:48
	s_nop 1
	s_cmp_eq_u32 s87, 0
	s_cbranch_scc1 .LV_sw0_c
	s_cmp_eq_u32 s87, 1
	s_cbranch_scc1 .LV_sw1_c
	s_cmp_eq_u32 s87, 2
	s_cbranch_scc1 .LV_sw2_c
	s_branch .LV_sw3_c

; __device__ __forceinline__ void peer_tile(const Args& A, LAS unsigned char* lds, int tile) {
;     ...
;         for (int tk = 0; tk < 4; ++tk) {
;             const size_t m = (size_t)tile * 64 + tb + tk; const int b = (int)(m >> 11);
;             float* orow = A.out + m * 1024 + 16 * lane;
;             const float* g2 = MOD + b * 6144 + 5120 + 16 * lane;
;             f32x4 xv[4]; float ss = 0.f;
; #pragma unroll
;             for (int j = 0; j < 4; ++j) { const f32x4 x1 = *(const f32x4*)(orow + 4 * j), gg = *(const f32x4*)(g2 + 4 * j);
;                 const f32x4 pe = (f32x4){oacc[tk][2 * j][0], oacc[tk][2 * j][1], oacc[tk][2 * j + 1][0], oacc[tk][2 * j + 1][1]};
;                 xv[j] = x1 + gg * pe; ss += (xv[j][0] * xv[j][0] + xv[j][1] * xv[j][1]) + (xv[j][2] * xv[j][2] + xv[j][3] * xv[j][3]); }
;             const float rstd = rsqrtf(wave_sum(ss) * (1.f / 1024.f) + 1e-6f);
; #pragma unroll
;             for (int j = 0; j < 4; ++j) { const f32x4 fg = *(const f32x4*)(A.final_g + 16 * lane + 4 * j); *(f32x4*)(orow + 4 * j) = xv[j] * rstd * fg; }
.LV_epi_t2_go:
	ds_read_b128 v[216:219], v211 offset:0
	ds_read_b128 v[220:223], v211 offset:1024
	ds_read_b128 v[224:227], v211 offset:2048
	ds_read_b128 v[228:231], v211 offset:3072
	s_waitcnt lgkmcnt(0)
	v_pk_fma_f32 v[32:33], v[32:33], v[216:217], v[192:193]
	v_pk_fma_f32 v[34:35], v[34:35], v[218:219], v[194:195]
	v_pk_fma_f32 v[36:37], v[36:37], v[220:221], v[196:197]
	v_pk_fma_f32 v[38:39], v[38:39], v[222:223], v[198:199]
	v_pk_fma_f32 v[40:41], v[40:41], v[224:225], v[200:201]
	v_pk_fma_f32 v[42:43], v[42:43], v[226:227], v[202:203]
	v_pk_fma_f32 v[44:45], v[44:45], v[228:229], v[204:205]
	v_pk_fma_f32 v[46:47], v[46:47], v[230:231], v[206:207]
	ds_read_b128 v[216:219], v211 offset:4096
	ds_read_b128 v[220:223], v211 offset:5120
	ds_read_b128 v[224:227], v211 offset:6144
	ds_read_b128 v[228:231], v211 offset:7168
	v_pk_mul_f32 v[208:209], v[32:33], v[32:33]
	v_pk_fma_f32 v[208:209], v[34:35], v[34:35], v[208:209]
	v_pk_fma_f32 v[208:209], v[36:37], v[36:37], v[208:209]
	v_pk_fma_f32 v[208:209], v[38:39], v[38:39], v[208:209]
	v_pk_fma_f32 v[208:209], v[40:41], v[40:41], v[208:209]
	v_pk_fma_f32 v[208:209], v[42:43], v[42:43], v[208:209]
	v_pk_fma_f32 v[208:209], v[44:45], v[44:45], v[208:209]
	v_pk_fma_f32 v[208:209], v[46:47], v[46:47], v[208:209]
	v_add_f32_e32 v208, v208, v209
	v_mov_b32_e32 v210, v208
	s_nop 1
	v_permlane32_swap_b32_e32 v208, v210
	v_add_f32_e32 v208, v208, v210
	v_mov_b32_e32 v210, v208
	s_nop 1
	v_permlane16_swap_b32_e32 v208, v210
	v_add_f32_e32 v208, v208, v210
	s_nop 1
	v_add_f32_dpp v208, v208, v208 quad_perm:[1,0,3,2] row_mask:0xf bank_mask:0xf bound_ctrl:1
	s_nop 1
	v_add_f32_dpp v208, v208, v208 quad_perm:[2,3,0,1] row_mask:0xf bank_mask:0xf bound_ctrl:1
	s_nop 1
	v_add_f32_dpp v208, v208, v208 row_half_mirror row_mask:0xf bank_mask:0xf bound_ctrl:1
	s_nop 1
	v_add_f32_dpp v208, v208, v208 row_mirror row_mask:0xf bank_mask:0xf bound_ctrl:1
	v_fmamk_f32 v208, v208, 0x3a800000, v243
	v_rsq_f32_e32 v208, v208
	s_waitcnt lgkmcnt(0)
	v_pk_mul_f32 v[192:193], v[32:33], v[208:209] op_sel_hi:[1,0]
	v_pk_mul_f32 v[194:195], v[34:35], v[208:209] op_sel_hi:[1,0]
	v_pk_mul_f32 v[196:197], v[36:37], v[208:209] op_sel_hi:[1,0]
	v_pk_mul_f32 v[198:199], v[38:39], v[208:209] op_sel_hi:[1,0]
	v_pk_mul_f32 v[200:201], v[40:41], v[208:209] op_sel_hi:[1,0]
	v_pk_mul_f32 v[202:203], v[42:43], v[208:209] op_sel_hi:[1,0]
	v_pk_mul_f32 v[204:205], v[44:45], v[208:209] op_sel_hi:[1,0]
	v_pk_mul_f32 v[206:207], v[46:47], v[208:209] op_sel_hi:[1,0]
	v_pk_mul_f32 v[192:193], v[216:217], v[192:193]
	v_pk_mul_f32 v[194:195], v[218:219], v[194:195]
	v_pk_mul_f32 v[196:197], v[220:221], v[196:197]
	v_pk_mul_f32 v[198:199], v[222:223], v[198:199]
	v_pk_mul_f32 v[200:201], v[224:225], v[200:201]
	v_pk_mul_f32 v[202:203], v[226:227], v[202:203]
	v_pk_mul_f32 v[204:205], v[228:229], v[204:205]
	v_pk_mul_f32 v[206:207], v[230:231], v[206:207]
	global_store_dwordx4 v246, v[192:195], s[24:25]
	global_store_dwordx4 v246, v[196:199], s[24:25] offset:16
	global_store_dwordx4 v246, v[200:203], s[24:25] offset:32
	global_store_dwordx4 v246, v[204:207], s[24:25] offset:48
	s_nop 1
	s_cmp_eq_u32 s87, 0
	s_cbranch_scc1 .LV_sw0_c
	s_cmp_eq_u32 s87, 1
	s_cbranch_scc1 .LV_sw1_c
	s_cmp_eq_u32 s87, 2
	s_cbranch_scc1 .LV_sw2_c
	s_branch .LV_sw3_c

; __device__ __forceinline__ void peer_tile(const Args& A, LAS unsigned char* lds, int tile) {
;     ...
;         for (int tk = 0; tk < 4; ++tk) {
;             const size_t m = (size_t)tile * 64 + tb + tk; const int b = (int)(m >> 11);
;             float* orow = A.out + m * 1024 + 16 * lane;
;             const float* g2 = MOD + b * 6144 + 5120 + 16 * lane;
;             f32x4 xv[4]; float ss = 0.f;
; #pragma unroll
;             for (int j = 0; j < 4; ++j) { const f32x4 x1 = *(const f32x4*)(orow + 4 * j), gg = *(const f32x4*)(g2 + 4 * j);
;                 const f32x4 pe = (f32x4){oacc[tk][2 * j][0], oacc[tk][2 * j][1], oacc[tk][2 * j + 1][0], oacc[tk][2 * j + 1][1]};
;                 xv[j] = x1 + gg * pe; ss += (xv[j][0] * xv[j][0] + xv[j][1] * xv[j][1]) + (xv[j][2] * xv[j][2] + xv[j][3] * xv[j][3]); }
;             const float rstd = rsqrtf(wave_sum(ss) * (1.f / 1024.f) + 1e-6f);
; #pragma unroll
;             for (int j = 0; j < 4; ++j) { const f32x4 fg = *(const f32x4*)(A.final_g + 16 * lane + 4 * j); *(f32x4*)(orow + 4 * j) = xv[j] * rstd * fg; }
.LV_epi_t3_go:
	ds_read_b128 v[216:219], v211 offset:0
	ds_read_b128 v[220:223], v211 offset:1024
	ds_read_b128 v[224:227], v211 offset:2048
	ds_read_b128 v[228:231], v211 offset:3072
	s_waitcnt lgkmcnt(0)
	v_pk_fma_f32 v[48:49], v[48:49], v[216:217], v[192:193]
	v_pk_fma_f32 v[50:51], v[50:51], v[218:219], v[194:195]
	v_pk_fma_f32 v[52:53], v[52:53], v[220:221], v[196:197]
	v_pk_fma_f32 v[54:55], v[54:55], v[222:223], v[198:199]
	v_pk_fma_f32 v[56:57], v[56:57], v[224:225], v[200:201]
	v_pk_fma_f32 v[58:59], v[58:59], v[226:227], v[202:203]
	v_pk_fma_f32 v[60:61], v[60:61], v[228:229], v[204:205]
	v_pk_fma_f32 v[62:63], v[62:63], v[230:231], v[206:207]
	ds_read_b128 v[216:219], v211 offset:4096
	ds_read_b128 v[220:223], v211 offset:5120
	ds_read_b128 v[224:227], v211 offset:6144
	ds_read_b128 v[228:231], v211 offset:7168
	v_pk_mul_f32 v[208:209], v[48:49], v[48:49]
	v_pk_fma_f32 v[208:209], v[50:51], v[50:51], v[208:209]
	v_pk_fma_f32 v[208:209], v[52:53], v[52:53], v[208:209]
	v_pk_fma_f32 v[208:209], v[54:55], v[54:55], v[208:209]
	v_pk_fma_f32 v[208:209], v[56:57], v[56:57], v[208:209]
	v_pk_fma_f32 v[208:209], v[58:59], v[58:59], v[208:209]
	v_pk_fma_f32 v[208:209], v[60:61], v[60:61], v[208:209]
	v_pk_fma_f32 v[208:209], v[62:63], v[62:63], v[208:209]
	v_add_f32_e32 v208, v208, v209
	v_mov_b32_e32 v210, v208
	s_nop 1
	v_permlane32_swap_b32_e32 v208, v210
	v_add_f32_e32 v208, v208, v210
	v_mov_b32_e32 v210, v208
	s_nop 1
	v_permlane16_swap_b32_e32 v208, v210
	v_add_f32_e32 v208, v208, v210
	s_nop 1
	v_add_f32_dpp v208, v208, v208 quad_perm:[1,0,3,2] row_mask:0xf bank_mask:0xf bound_ctrl:1
	s_nop 1
	v_add_f32_dpp v208, v208, v208 quad_perm:[2,3,0,1] row_mask:0xf bank_mask:0xf bound_ctrl:1
	s_nop 1
	v_add_f32_dpp v208, v208, v208 row_half_mirror row_mask:0xf bank_mask:0xf bound_ctrl:1
	s_nop 1
	v_add_f32_dpp v208, v208, v208 row_mirror row_mask:0xf bank_mask:0xf bound_ctrl:1
	v_fmamk_f32 v208, v208, 0x3a800000, v243
	v_rsq_f32_e32 v208, v208
	s_waitcnt lgkmcnt(0)
	v_pk_mul_f32 v[192:193], v[48:49], v[208:209] op_sel_hi:[1,0]
	v_pk_mul_f32 v[194:195], v[50:51], v[208:209] op_sel_hi:[1,0]
	v_pk_mul_f32 v[196:197], v[52:53], v[208:209] op_sel_hi:[1,0]
	v_pk_mul_f32 v[198:199], v[54:55], v[208:209] op_sel_hi:[1,0]
	v_pk_mul_f32 v[200:201], v[56:57], v[208:209] op_sel_hi:[1,0]
	v_pk_mul_f32 v[202:203], v[58:59], v[208:209] op_sel_hi:[1,0]
	v_pk_mul_f32 v[204:205], v[60:61], v[208:209] op_sel_hi:[1,0]
	v_pk_mul_f32 v[206:207], v[62:63], v[208:209] op_sel_hi:[1,0]
	v_pk_mul_f32 v[192:193], v[216:217], v[192:193]
	v_pk_mul_f32 v[194:195], v[218:219], v[194:195]
	v_pk_mul_f32 v[196:197], v[220:221], v[196:197]
	v_pk_mul_f32 v[198:199], v[222:223], v[198:199]
	v_pk_mul_f32 v[200:201], v[224:225], v[200:201]
	v_pk_mul_f32 v[202:203], v[226:227], v[202:203]
	v_pk_mul_f32 v[204:205], v[228:229], v[204:205]
	v_pk_mul_f32 v[206:207], v[230:231], v[206:207]
	global_store_dwordx4 v246, v[192:195], s[24:25]
	global_store_dwordx4 v246, v[196:199], s[24:25] offset:16
	global_store_dwordx4 v246, v[200:203], s[24:25] offset:32
	global_store_dwordx4 v246, v[204:207], s[24:25] offset:48
	s_nop 1
	s_cmp_eq_u32 s87, 0
	s_cbranch_scc1 .LV_sw0_c
	s_cmp_eq_u32 s87, 1
	s_cbranch_scc1 .LV_sw1_c
	s_cmp_eq_u32 s87, 2
	s_cbranch_scc1 .LV_sw2_c
	s_branch .LV_sw3_c

; __device__ __forceinline__ void peer_tile(const Args& A, LAS unsigned char* lds, int tile) {
;     ...
;         for (int tk = 0; tk < 4; ++tk) {
;             const size_t m = (size_t)tile * 64 + tb + tk; const int b = (int)(m >> 11);
;             float* orow = A.out + m * 1024 + 16 * lane;
;             const float* g2 = MOD + b * 6144 + 5120 + 16 * lane;
;             f32x4 xv[4]; float ss = 0.f;
; #pragma unroll
;             for (int j = 0; j < 4; ++j) { const f32x4 x1 = *(const f32x4*)(orow + 4 * j), gg = *(const f32x4*)(g2 + 4 * j);
;                 const f32x4 pe = (f32x4){oacc[tk][2 * j][0], oacc[tk][2 * j][1], oacc[tk][2 * j + 1][0], oacc[tk][2 * j + 1][1]};
;                 xv[j] = x1 + gg * pe; ss += (xv[j][0] * xv[j][0] + xv[j][1] * xv[j][1]) + (xv[j][2] * xv[j][2] + xv[j][3] * xv[j][3]); }
;             const float rstd = rsqrtf(wave_sum(ss) * (1.f / 1024.f) + 1e-6f);
; #pragma unroll
;             for (int j = 0; j < 4; ++j) { const f32x4 fg = *(const f32x4*)(A.final_g + 16 * lane + 4 * j); *(f32x4*)(orow + 4 * j) = xv[j] * rstd * fg; }
.LV_epi_t4_go:
	ds_read_b128 v[216:219], v211 offset:0
	ds_read_b128 v[220:223], v211 offset:1024
	ds_read_b128 v[224:227], v211 offset:2048
	ds_read_b128 v[228:231], v211 offset:3072
	s_waitcnt lgkmcnt(0)
	v_pk_fma_f32 v[64:65], v[64:65], v[216:217], v[192:193]
	v_pk_fma_f32 v[66:67], v[66:67], v[218:219], v[194:195]
	v_pk_fma_f32 v[68:69], v[68:69], v[220:221], v[196:197]
	v_pk_fma_f32 v[70:71], v[70:71], v[222:223], v[198:199]
	v_pk_fma_f32 v[72:73], v[72:73], v[224:225], v[200:201]
	v_pk_fma_f32 v[74:75], v[74:75], v[226:227], v[202:203]
	v_pk_fma_f32 v[76:77], v[76:77], v[228:229], v[204:205]
	v_pk_fma_f32 v[78:79], v[78:79], v[230:231], v[206:207]
	ds_read_b128 v[216:219], v211 offset:4096
	ds_read_b128 v[220:223], v211 offset:5120
	ds_read_b128 v[224:227], v211 offset:6144
	ds_read_b128 v[228:231], v211 offset:7168
	v_pk_mul_f32 v[208:209], v[64:65], v[64:65]
	v_pk_fma_f32 v[208:209], v[66:67], v[66:67], v[208:209]
	v_pk_fma_f32 v[208:209], v[68:69], v[68:69], v[208:209]
	v_pk_fma_f32 v[208:209], v[70:71], v[70:71], v[208:209]
	v_pk_fma_f32 v[208:209], v[72:73], v[72:73], v[208:209]
	v_pk_fma_f32 v[208:209], v[74:75], v[74:75], v[208:209]
	v_pk_fma_f32 v[208:209], v[76:77], v[76:77], v[208:209]
	v_pk_fma_f32 v[208:209], v[78:79], v[78:79], v[208:209]
	v_add_f32_e32 v208, v208, v209
	v_mov_b32_e32 v210, v208
	s_nop 1
	v_permlane32_swap_b32_e32 v208, v210
	v_add_f32_e32 v208, v208, v210
	v_mov_b32_e32 v210, v208
	s_nop 1
	v_permlane16_swap_b32_e32 v208, v210
	v_add_f32_e32 v208, v208, v210
	s_nop 1
	v_add_f32_dpp v208, v208, v208 quad_perm:[1,0,3,2] row_mask:0xf bank_mask:0xf bound_ctrl:1
	s_nop 1
	v_add_f32_dpp v208, v208, v208 quad_perm:[2,3,0,1] row_mask:0xf bank_mask:0xf bound_ctrl:1
	s_nop 1
	v_add_f32_dpp v208, v208, v208 row_half_mirror row_mask:0xf bank_mask:0xf bound_ctrl:1
	s_nop 1
	v_add_f32_dpp v208, v208, v208 row_mirror row_mask:0xf bank_mask:0xf bound_ctrl:1
	v_fmamk_f32 v208, v208, 0x3a800000, v243
	v_rsq_f32_e32 v208, v208
	s_waitcnt lgkmcnt(0)
	v_pk_mul_f32 v[192:193], v[64:65], v[208:209] op_sel_hi:[1,0]
	v_pk_mul_f32 v[194:195], v[66:67], v[208:209] op_sel_hi:[1,0]
	v_pk_mul_f32 v[196:197], v[68:69], v[208:209] op_sel_hi:[1,0]
	v_pk_mul_f32 v[198:199], v[70:71], v[208:209] op_sel_hi:[1,0]
	v_pk_mul_f32 v[200:201], v[72:73], v[208:209] op_sel_hi:[1,0]
	v_pk_mul_f32 v[202:203], v[74:75], v[208:209] op_sel_hi:[1,0]
	v_pk_mul_f32 v[204:205], v[76:77], v[208:209] op_sel_hi:[1,0]
	v_pk_mul_f32 v[206:207], v[78:79], v[208:209] op_sel_hi:[1,0]
	v_pk_mul_f32 v[192:193], v[216:217], v[192:193]
	v_pk_mul_f32 v[194:195], v[218:219], v[194:195]
	v_pk_mul_f32 v[196:197], v[220:221], v[196:197]
	v_pk_mul_f32 v[198:199], v[222:223], v[198:199]
	v_pk_mul_f32 v[200:201], v[224:225], v[200:201]
	v_pk_mul_f32 v[202:203], v[226:227], v[202:203]
	v_pk_mul_f32 v[204:205], v[228:229], v[204:205]
	v_pk_mul_f32 v[206:207], v[230:231], v[206:207]
	global_store_dwordx4 v246, v[192:195], s[24:25]
	global_store_dwordx4 v246, v[196:199], s[24:25] offset:16
	global_store_dwordx4 v246, v[200:203], s[24:25] offset:32
	global_store_dwordx4 v246, v[204:207], s[24:25] offset:48
	s_nop 1
	s_cmp_eq_u32 s87, 0
	s_cbranch_scc1 .LV_sw0_c
	s_cmp_eq_u32 s87, 1
	s_cbranch_scc1 .LV_sw1_c
	s_cmp_eq_u32 s87, 2
	s_cbranch_scc1 .LV_sw2_c
	s_branch .LV_sw3_c

; __device__ __forceinline__ void peer_tile(const Args& A, LAS unsigned char* lds, int tile) {
;     ...
;         for (int tk = 0; tk < 4; ++tk) {
;             const size_t m = (size_t)tile * 64 + tb + tk; const int b = (int)(m >> 11);
;             float* orow = A.out + m * 1024 + 16 * lane;
;             const float* g2 = MOD + b * 6144 + 5120 + 16 * lane;
;             f32x4 xv[4]; float ss = 0.f;
; #pragma unroll
;             for (int j = 0; j < 4; ++j) { const f32x4 x1 = *(const f32x4*)(orow + 4 * j), gg = *(const f32x4*)(g2 + 4 * j);
;                 const f32x4 pe = (f32x4){oacc[tk][2 * j][0], oacc[tk][2 * j][1], oacc[tk][2 * j + 1][0], oacc[tk][2 * j + 1][1]};
;                 xv[j] = x1 + gg * pe; ss += (xv[j][0] * xv[j][0] + xv[j][1] * xv[j][1]) + (xv[j][2] * xv[j][2] + xv[j][3] * xv[j][3]); }
;             const float rstd = rsqrtf(wave_sum(ss) * (1.f / 1024.f) + 1e-6f);
; #pragma unroll
;             for (int j = 0; j < 4; ++j) { const f32x4 fg = *(const f32x4*)(A.final_g + 16 * lane + 4 * j); *(f32x4*)(orow + 4 * j) = xv[j] * rstd * fg; }
.LV_epi_t5_go:
	ds_read_b128 v[216:219], v211 offset:0
	ds_read_b128 v[220:223], v211 offset:1024
	ds_read_b128 v[224:227], v211 offset:2048
	ds_read_b128 v[228:231], v211 offset:3072
	s_waitcnt lgkmcnt(0)
	v_pk_fma_f32 v[80:81], v[80:81], v[216:217], v[192:193]
	v_pk_fma_f32 v[82:83], v[82:83], v[218:219], v[194:195]
	v_pk_fma_f32 v[84:85], v[84:85], v[220:221], v[196:197]
	v_pk_fma_f32 v[86:87], v[86:87], v[222:223], v[198:199]
	v_pk_fma_f32 v[88:89], v[88:89], v[224:225], v[200:201]
	v_pk_fma_f32 v[90:91], v[90:91], v[226:227], v[202:203]
	v_pk_fma_f32 v[92:93], v[92:93], v[228:229], v[204:205]
	v_pk_fma_f32 v[94:95], v[94:95], v[230:231], v[206:207]
	ds_read_b128 v[216:219], v211 offset:4096
	ds_read_b128 v[220:223], v211 offset:5120
	ds_read_b128 v[224:227], v211 offset:6144
	ds_read_b128 v[228:231], v211 offset:7168
	v_pk_mul_f32 v[208:209], v[80:81], v[80:81]
	v_pk_fma_f32 v[208:209], v[82:83], v[82:83], v[208:209]
	v_pk_fma_f32 v[208:209], v[84:85], v[84:85], v[208:209]
	v_pk_fma_f32 v[208:209], v[86:87], v[86:87], v[208:209]
	v_pk_fma_f32 v[208:209], v[88:89], v[88:89], v[208:209]
	v_pk_fma_f32 v[208:209], v[90:91], v[90:91], v[208:209]
	v_pk_fma_f32 v[208:209], v[92:93], v[92:93], v[208:209]
	v_pk_fma_f32 v[208:209], v[94:95], v[94:95], v[208:209]
	v_add_f32_e32 v208, v208, v209
	v_mov_b32_e32 v210, v208
	s_nop 1
	v_permlane32_swap_b32_e32 v208, v210
	v_add_f32_e32 v208, v208, v210
	v_mov_b32_e32 v210, v208
	s_nop 1
	v_permlane16_swap_b32_e32 v208, v210
	v_add_f32_e32 v208, v208, v210
	s_nop 1
	v_add_f32_dpp v208, v208, v208 quad_perm:[1,0,3,2] row_mask:0xf bank_mask:0xf bound_ctrl:1
	s_nop 1
	v_add_f32_dpp v208, v208, v208 quad_perm:[2,3,0,1] row_mask:0xf bank_mask:0xf bound_ctrl:1
	s_nop 1
	v_add_f32_dpp v208, v208, v208 row_half_mirror row_mask:0xf bank_mask:0xf bound_ctrl:1
	s_nop 1
	v_add_f32_dpp v208, v208, v208 row_mirror row_mask:0xf bank_mask:0xf bound_ctrl:1
	v_fmamk_f32 v208, v208, 0x3a800000, v243
	v_rsq_f32_e32 v208, v208
	s_waitcnt lgkmcnt(0)
	v_pk_mul_f32 v[192:193], v[80:81], v[208:209] op_sel_hi:[1,0]
	v_pk_mul_f32 v[194:195], v[82:83], v[208:209] op_sel_hi:[1,0]
	v_pk_mul_f32 v[196:197], v[84:85], v[208:209] op_sel_hi:[1,0]
	v_pk_mul_f32 v[198:199], v[86:87], v[208:209] op_sel_hi:[1,0]
	v_pk_mul_f32 v[200:201], v[88:89], v[208:209] op_sel_hi:[1,0]
	v_pk_mul_f32 v[202:203], v[90:91], v[208:209] op_sel_hi:[1,0]
	v_pk_mul_f32 v[204:205], v[92:93], v[208:209] op_sel_hi:[1,0]
	v_pk_mul_f32 v[206:207], v[94:95], v[208:209] op_sel_hi:[1,0]
	v_pk_mul_f32 v[192:193], v[216:217], v[192:193]
	v_pk_mul_f32 v[194:195], v[218:219], v[194:195]
	v_pk_mul_f32 v[196:197], v[220:221], v[196:197]
	v_pk_mul_f32 v[198:199], v[222:223], v[198:199]
	v_pk_mul_f32 v[200:201], v[224:225], v[200:201]
	v_pk_mul_f32 v[202:203], v[226:227], v[202:203]
	v_pk_mul_f32 v[204:205], v[228:229], v[204:205]
	v_pk_mul_f32 v[206:207], v[230:231], v[206:207]
	global_store_dwordx4 v246, v[192:195], s[24:25]
	global_store_dwordx4 v246, v[196:199], s[24:25] offset:16
	global_store_dwordx4 v246, v[200:203], s[24:25] offset:32
	global_store_dwordx4 v246, v[204:207], s[24:25] offset:48
	s_nop 1
	s_cmp_eq_u32 s87, 0
	s_cbranch_scc1 .LV_sw0_c
	s_cmp_eq_u32 s87, 1
	s_cbranch_scc1 .LV_sw1_c
	s_cmp_eq_u32 s87, 2
	s_cbranch_scc1 .LV_sw2_c
	s_branch .LV_sw3_c

; __device__ __forceinline__ void peer_tile(const Args& A, LAS unsigned char* lds, int tile) {
;     ...
;         for (int tk = 0; tk < 4; ++tk) {
;             const size_t m = (size_t)tile * 64 + tb + tk; const int b = (int)(m >> 11);
;             float* orow = A.out + m * 1024 + 16 * lane;
;             const float* g2 = MOD + b * 6144 + 5120 + 16 * lane;
;             f32x4 xv[4]; float ss = 0.f;
; #pragma unroll
;             for (int j = 0; j < 4; ++j) { const f32x4 x1 = *(const f32x4*)(orow + 4 * j), gg = *(const f32x4*)(g2 + 4 * j);
;                 const f32x4 pe = (f32x4){oacc[tk][2 * j][0], oacc[tk][2 * j][1], oacc[tk][2 * j + 1][0], oacc[tk][2 * j + 1][1]};
;                 xv[j] = x1 + gg * pe; ss += (xv[j][0] * xv[j][0] + xv[j][1] * xv[j][1]) + (xv[j][2] * xv[j][2] + xv[j][3] * xv[j][3]); }
;             const float rstd = rsqrtf(wave_sum(ss) * (1.f / 1024.f) + 1e-6f);
; #pragma unroll
;             for (int j = 0; j < 4; ++j) { const f32x4 fg = *(const f32x4*)(A.final_g + 16 * lane + 4 * j); *(f32x4*)(orow + 4 * j) = xv[j] * rstd * fg; }
.LV_epi_t6_go:
	ds_read_b128 v[216:219], v211 offset:0
	ds_read_b128 v[220:223], v211 offset:1024
	ds_read_b128 v[224:227], v211 offset:2048
	ds_read_b128 v[228:231], v211 offset:3072
	s_waitcnt lgkmcnt(0)
	v_pk_fma_f32 v[96:97], v[96:97], v[216:217], v[192:193]
	v_pk_fma_f32 v[98:99], v[98:99], v[218:219], v[194:195]
	v_pk_fma_f32 v[100:101], v[100:101], v[220:221], v[196:197]
	v_pk_fma_f32 v[102:103], v[102:103], v[222:223], v[198:199]
	v_pk_fma_f32 v[104:105], v[104:105], v[224:225], v[200:201]
	v_pk_fma_f32 v[106:107], v[106:107], v[226:227], v[202:203]
	v_pk_fma_f32 v[108:109], v[108:109], v[228:229], v[204:205]
	v_pk_fma_f32 v[110:111], v[110:111], v[230:231], v[206:207]
	ds_read_b128 v[216:219], v211 offset:4096
	ds_read_b128 v[220:223], v211 offset:5120
	ds_read_b128 v[224:227], v211 offset:6144
	ds_read_b128 v[228:231], v211 offset:7168
	v_pk_mul_f32 v[208:209], v[96:97], v[96:97]
	v_pk_fma_f32 v[208:209], v[98:99], v[98:99], v[208:209]
	v_pk_fma_f32 v[208:209], v[100:101], v[100:101], v[208:209]
	v_pk_fma_f32 v[208:209], v[102:103], v[102:103], v[208:209]
	v_pk_fma_f32 v[208:209], v[104:105], v[104:105], v[208:209]
	v_pk_fma_f32 v[208:209], v[106:107], v[106:107], v[208:209]
	v_pk_fma_f32 v[208:209], v[108:109], v[108:109], v[208:209]
	v_pk_fma_f32 v[208:209], v[110:111], v[110:111], v[208:209]
	v_add_f32_e32 v208, v208, v209
	v_mov_b32_e32 v210, v208
	s_nop 1
	v_permlane32_swap_b32_e32 v208, v210
	v_add_f32_e32 v208, v208, v210
	v_mov_b32_e32 v210, v208
	s_nop 1
	v_permlane16_swap_b32_e32 v208, v210
	v_add_f32_e32 v208, v208, v210
	s_nop 1
	v_add_f32_dpp v208, v208, v208 quad_perm:[1,0,3,2] row_mask:0xf bank_mask:0xf bound_ctrl:1
	s_nop 1
	v_add_f32_dpp v208, v208, v208 quad_perm:[2,3,0,1] row_mask:0xf bank_mask:0xf bound_ctrl:1
	s_nop 1
	v_add_f32_dpp v208, v208, v208 row_half_mirror row_mask:0xf bank_mask:0xf bound_ctrl:1
	s_nop 1
	v_add_f32_dpp v208, v208, v208 row_mirror row_mask:0xf bank_mask:0xf bound_ctrl:1
	v_fmamk_f32 v208, v208, 0x3a800000, v243
	v_rsq_f32_e32 v208, v208
	s_waitcnt lgkmcnt(0)
	v_pk_mul_f32 v[192:193], v[96:97], v[208:209] op_sel_hi:[1,0]
	v_pk_mul_f32 v[194:195], v[98:99], v[208:209] op_sel_hi:[1,0]
	v_pk_mul_f32 v[196:197], v[100:101], v[208:209] op_sel_hi:[1,0]
	v_pk_mul_f32 v[198:199], v[102:103], v[208:209] op_sel_hi:[1,0]
	v_pk_mul_f32 v[200:201], v[104:105], v[208:209] op_sel_hi:[1,0]
	v_pk_mul_f32 v[202:203], v[106:107], v[208:209] op_sel_hi:[1,0]
	v_pk_mul_f32 v[204:205], v[108:109], v[208:209] op_sel_hi:[1,0]
	v_pk_mul_f32 v[206:207], v[110:111], v[208:209] op_sel_hi:[1,0]
	v_pk_mul_f32 v[192:193], v[216:217], v[192:193]
	v_pk_mul_f32 v[194:195], v[218:219], v[194:195]
	v_pk_mul_f32 v[196:197], v[220:221], v[196:197]
	v_pk_mul_f32 v[198:199], v[222:223], v[198:199]
	v_pk_mul_f32 v[200:201], v[224:225], v[200:201]
	v_pk_mul_f32 v[202:203], v[226:227], v[202:203]
	v_pk_mul_f32 v[204:205], v[228:229], v[204:205]
	v_pk_mul_f32 v[206:207], v[230:231], v[206:207]
	global_store_dwordx4 v246, v[192:195], s[24:25]
	global_store_dwordx4 v246, v[196:199], s[24:25] offset:16
	global_store_dwordx4 v246, v[200:203], s[24:25] offset:32
	global_store_dwordx4 v246, v[204:207], s[24:25] offset:48
	s_nop 1
	s_cmp_eq_u32 s87, 0
	s_cbranch_scc1 .LV_sw0_c
	s_cmp_eq_u32 s87, 1
	s_cbranch_scc1 .LV_sw1_c
	s_cmp_eq_u32 s87, 2
	s_cbranch_scc1 .LV_sw2_c
	s_branch .LV_sw3_c

; __device__ __forceinline__ void peer_tile(const Args& A, LAS unsigned char* lds, int tile) {
;     ...
;         for (int tk = 0; tk < 4; ++tk) {
;             const size_t m = (size_t)tile * 64 + tb + tk; const int b = (int)(m >> 11);
;             float* orow = A.out + m * 1024 + 16 * lane;
;             const float* g2 = MOD + b * 6144 + 5120 + 16 * lane;
;             f32x4 xv[4]; float ss = 0.f;
; #pragma unroll
;             for (int j = 0; j < 4; ++j) { const f32x4 x1 = *(const f32x4*)(orow + 4 * j), gg = *(const f32x4*)(g2 + 4 * j);
;                 const f32x4 pe = (f32x4){oacc[tk][2 * j][0], oacc[tk][2 * j][1], oacc[tk][2 * j + 1][0], oacc[tk][2 * j + 1][1]};
;                 xv[j] = x1 + gg * pe; ss += (xv[j][0] * xv[j][0] + xv[j][1] * xv[j][1]) + (xv[j][2] * xv[j][2] + xv[j][3] * xv[j][3]); }
;             const float rstd = rsqrtf(wave_sum(ss) * (1.f / 1024.f) + 1e-6f);
; #pragma unroll
;             for (int j = 0; j < 4; ++j) { const f32x4 fg = *(const f32x4*)(A.final_g + 16 * lane + 4 * j); *(f32x4*)(orow + 4 * j) = xv[j] * rstd * fg; }
.LV_epi_t7_go:
	ds_read_b128 v[216:219], v211 offset:0
	ds_read_b128 v[220:223], v211 offset:1024
	ds_read_b128 v[224:227], v211 offset:2048
	ds_read_b128 v[228:231], v211 offset:3072
	s_waitcnt lgkmcnt(0)
	v_pk_fma_f32 v[112:113], v[112:113], v[216:217], v[192:193]
	v_pk_fma_f32 v[114:115], v[114:115], v[218:219], v[194:195]
	v_pk_fma_f32 v[116:117], v[116:117], v[220:221], v[196:197]
	v_pk_fma_f32 v[118:119], v[118:119], v[222:223], v[198:199]
	v_pk_fma_f32 v[120:121], v[120:121], v[224:225], v[200:201]
	v_pk_fma_f32 v[122:123], v[122:123], v[226:227], v[202:203]
	v_pk_fma_f32 v[124:125], v[124:125], v[228:229], v[204:205]
	v_pk_fma_f32 v[126:127], v[126:127], v[230:231], v[206:207]
	ds_read_b128 v[216:219], v211 offset:4096
	ds_read_b128 v[220:223], v211 offset:5120
	ds_read_b128 v[224:227], v211 offset:6144
	ds_read_b128 v[228:231], v211 offset:7168
	v_pk_mul_f32 v[208:209], v[112:113], v[112:113]
	v_pk_fma_f32 v[208:209], v[114:115], v[114:115], v[208:209]
	v_pk_fma_f32 v[208:209], v[116:117], v[116:117], v[208:209]
	v_pk_fma_f32 v[208:209], v[118:119], v[118:119], v[208:209]
	v_pk_fma_f32 v[208:209], v[120:121], v[120:121], v[208:209]
	v_pk_fma_f32 v[208:209], v[122:123], v[122:123], v[208:209]
	v_pk_fma_f32 v[208:209], v[124:125], v[124:125], v[208:209]
	v_pk_fma_f32 v[208:209], v[126:127], v[126:127], v[208:209]
	v_add_f32_e32 v208, v208, v209
	v_mov_b32_e32 v210, v208
	s_nop 1
	v_permlane32_swap_b32_e32 v208, v210
	v_add_f32_e32 v208, v208, v210
	v_mov_b32_e32 v210, v208
	s_nop 1
	v_permlane16_swap_b32_e32 v208, v210
	v_add_f32_e32 v208, v208, v210
	s_nop 1
	v_add_f32_dpp v208, v208, v208 quad_perm:[1,0,3,2] row_mask:0xf bank_mask:0xf bound_ctrl:1
	s_nop 1
	v_add_f32_dpp v208, v208, v208 quad_perm:[2,3,0,1] row_mask:0xf bank_mask:0xf bound_ctrl:1
	s_nop 1
	v_add_f32_dpp v208, v208, v208 row_half_mirror row_mask:0xf bank_mask:0xf bound_ctrl:1
	s_nop 1
	v_add_f32_dpp v208, v208, v208 row_mirror row_mask:0xf bank_mask:0xf bound_ctrl:1
	v_fmamk_f32 v208, v208, 0x3a800000, v243
	v_rsq_f32_e32 v208, v208
	s_waitcnt lgkmcnt(0)
	v_pk_mul_f32 v[192:193], v[112:113], v[208:209] op_sel_hi:[1,0]
	v_pk_mul_f32 v[194:195], v[114:115], v[208:209] op_sel_hi:[1,0]
	v_pk_mul_f32 v[196:197], v[116:117], v[208:209] op_sel_hi:[1,0]
	v_pk_mul_f32 v[198:199], v[118:119], v[208:209] op_sel_hi:[1,0]
	v_pk_mul_f32 v[200:201], v[120:121], v[208:209] op_sel_hi:[1,0]
	v_pk_mul_f32 v[202:203], v[122:123], v[208:209] op_sel_hi:[1,0]
	v_pk_mul_f32 v[204:205], v[124:125], v[208:209] op_sel_hi:[1,0]
	v_pk_mul_f32 v[206:207], v[126:127], v[208:209] op_sel_hi:[1,0]
	v_pk_mul_f32 v[192:193], v[216:217], v[192:193]
	v_pk_mul_f32 v[194:195], v[218:219], v[194:195]
	v_pk_mul_f32 v[196:197], v[220:221], v[196:197]
	v_pk_mul_f32 v[198:199], v[222:223], v[198:199]
	v_pk_mul_f32 v[200:201], v[224:225], v[200:201]
	v_pk_mul_f32 v[202:203], v[226:227], v[202:203]
	v_pk_mul_f32 v[204:205], v[228:229], v[204:205]
	v_pk_mul_f32 v[206:207], v[230:231], v[206:207]
	global_store_dwordx4 v246, v[192:195], s[24:25]
	global_store_dwordx4 v246, v[196:199], s[24:25] offset:16
	global_store_dwordx4 v246, v[200:203], s[24:25] offset:32
	global_store_dwordx4 v246, v[204:207], s[24:25] offset:48
	s_nop 1
	s_cmp_eq_u32 s87, 0
	s_cbranch_scc1 .LV_sw0_c
	s_cmp_eq_u32 s87, 1
	s_cbranch_scc1 .LV_sw1_c
	s_cmp_eq_u32 s87, 2
	s_cbranch_scc1 .LV_sw2_c
	s_branch .LV_sw3_c
.LV_done:
	s_waitcnt vmcnt(0) lgkmcnt(0)
	v_mov_b32_e32 v113, 0
	v_mbcnt_lo_u32_b32 v215, -1, 0
	v_mbcnt_hi_u32_b32 v215, -1, v215
	v_and_b32_e32 v216, 64, v215
	v_add_u32_e32 v216, 64, v216
	v_xor_b32_e32 v217, 16, v215
	v_xor_b32_e32 v218, 32, v215
	s_branch .LBB0_698

